# prep rows: the remaining lane^32/^16/^8 exchanges of the 64-lane reductions via permlane swaps and DPP row_ror (6 sites)
# baseline (speedup 1.0000x reference)
.LBB0_600:
	s_or_b64 exec, exec, s[56:57]
	v_lshlrev_b32_e32 v52, 16, v48
	v_and_b32_e32 v53, 0xffff0000, v48
	v_pk_mul_f32 v[56:57], v[52:53], v[52:53]
	v_lshlrev_b32_e32 v48, 16, v49
	v_and_b32_e32 v49, 0xffff0000, v49
	v_pk_mul_f32 v[58:59], v[48:49], v[48:49]
	v_add_f32_e32 v56, v56, v57
	v_lshlrev_b32_e32 v54, 16, v50
	v_and_b32_e32 v55, 0xffff0000, v50
	v_add_f32_e32 v56, v58, v56
	v_pk_mul_f32 v[60:61], v[54:55], v[54:55]
	v_add_f32_e32 v56, v59, v56
	v_lshlrev_b32_e32 v50, 16, v51
	v_and_b32_e32 v51, 0xffff0000, v51
	v_add_f32_e32 v56, v60, v56
	v_pk_mul_f32 v[62:63], v[50:51], v[50:51]
	v_add_f32_e32 v56, v61, v56
	v_add_f32_e32 v56, v62, v56
	v_cmp_lt_i32_e32 vcc, v180, v182
	v_add_f32_e32 v56, v63, v56
	v_cndmask_b32_e64 v56, 0, v56, s[42:43]
	v_cndmask_b32_e32 v57, v179, v180, vcc
	v_lshlrev_b32_e32 v58, 2, v57
	v_mov_b32_e32 v57, v56
	s_nop 1
	v_permlane32_swap_b32_e32 v57, v56
	s_nop 1
	v_cmp_lt_i32_e32 vcc, v183, v182
	s_waitcnt lgkmcnt(0)
	v_add_f32_e32 v56, v56, v57
	v_cndmask_b32_e32 v57, v179, v183, vcc
	v_lshlrev_b32_e32 v59, 2, v57
	v_mov_b32_e32 v57, v56
	s_nop 1
	v_permlane16_swap_b32_e32 v57, v56
	s_nop 1
	v_cmp_lt_i32_e32 vcc, v184, v182
	s_waitcnt lgkmcnt(0)
	v_add_f32_e32 v56, v56, v57
	v_cndmask_b32_e32 v57, v179, v184, vcc
	v_lshlrev_b32_e32 v60, 2, v57
	s_nop 1
	v_mov_b32_dpp v57, v56 row_ror:8 row_mask:0xf bank_mask:0xf
	s_waitcnt lgkmcnt(0)
	v_add_f32_e32 v56, v56, v57
	s_nop 1
	v_mov_b32_dpp v57, v56 row_shl:4 row_mask:0xf bank_mask:0x5
	v_mov_b32_dpp v57, v56 row_shr:4 row_mask:0xf bank_mask:0xa
	s_waitcnt lgkmcnt(0)
	v_add_f32_e32 v56, v56, v57
	s_nop 1
	v_mov_b32_dpp v57, v56 quad_perm:[2,3,0,1] row_mask:0xf bank_mask:0xf
	s_waitcnt lgkmcnt(0)
	v_add_f32_e32 v56, v56, v57
	s_nop 1
	v_mov_b32_dpp v57, v56 quad_perm:[1,0,3,2] row_mask:0xf bank_mask:0xf
	s_and_saveexec_b64 s[56:57], s[42:43]
	s_cbranch_execz .LBB0_602
	ds_read_b128 v[62:65], v162 offset:18944
	ds_read_b128 v[66:69], v162 offset:18960
	s_waitcnt lgkmcnt(0)
	v_add_f32_e32 v56, v56, v57
	v_fmamk_f32 v56, v56, 0x3b2aaaab, v174
	v_rsq_f32_e32 v56, v56
	v_readlane_b32 s80, v254, 48
	v_readlane_b32 s84, v254, 52
	v_readlane_b32 s85, v254, 53
	v_pk_mul_f32 v[52:53], v[56:57], v[52:53] op_sel_hi:[0,1]
	v_pk_mul_f32 v[48:49], v[56:57], v[48:49] op_sel_hi:[0,1]
	v_pk_mul_f32 v[54:55], v[56:57], v[54:55] op_sel_hi:[0,1]
	v_pk_mul_f32 v[50:51], v[56:57], v[50:51] op_sel_hi:[0,1]
	v_readlane_b32 s81, v254, 49
	v_readlane_b32 s82, v254, 50
	v_readlane_b32 s83, v254, 51
	v_readlane_b32 s86, v254, 54
	v_readlane_b32 s87, v254, 55
	s_waitcnt lgkmcnt(0)
	v_pk_mul_f32 v[52:53], v[52:53], v[62:63]
	v_pk_mul_f32 v[56:57], v[48:49], v[64:65]
	s_nop 0
	v_pk_mul_f32 v[54:55], v[54:55], v[66:67]
	v_pk_mul_f32 v[62:63], v[50:51], v[68:69]
	v_cvt_pk_bf16_f32 v48, v52, v53
	v_cvt_pk_bf16_f32 v49, v56, v57
	v_cvt_pk_bf16_f32 v50, v54, v55
	v_cvt_pk_bf16_f32 v51, v62, v63
	v_lshl_add_u64 v[52:53], s[84:85], 0, v[120:121]
	global_store_dwordx4 v[52:53], v[48:51], off
.LBB0_602:
	s_or_b64 exec, exec, s[56:57]
	s_nop 0
	v_lshlrev_b32_e32 v48, 16, v44
	v_and_b32_e32 v49, 0xffff0000, v44
	v_lshlrev_b32_e32 v54, 16, v47
	v_and_b32_e32 v55, 0xffff0000, v47
	v_lshlrev_b32_e32 v56, 16, v46
	s_waitcnt lgkmcnt(0)
	v_and_b32_e32 v57, 0xffff0000, v46
	v_lshlrev_b32_e32 v46, 16, v45
	v_and_b32_e32 v47, 0xffff0000, v45
	v_pk_mul_f32 v[44:45], v[48:49], v[48:49]
	v_pk_mul_f32 v[62:63], v[46:47], v[46:47]
	v_add_f32_e32 v44, v44, v45
	v_add_f32_e32 v44, v62, v44
	v_pk_mul_f32 v[52:53], v[56:57], v[56:57]
	v_add_f32_e32 v44, v63, v44
	v_add_f32_e32 v44, v52, v44
	v_pk_mul_f32 v[50:51], v[54:55], v[54:55]
	v_add_f32_e32 v44, v53, v44
	v_add_f32_e32 v44, v50, v44
	v_add_f32_e32 v44, v51, v44
	v_cndmask_b32_e64 v44, 0, v44, s[38:39]
	v_mov_b32_e32 v45, v44
	s_nop 1
	v_permlane32_swap_b32_e32 v45, v44
	s_nop 1
	v_mul_i32_i24_e32 v50, 0xa00, v147
	s_movk_i32 s2, 0x1200
	v_add3_u32 v50, v143, v50, s2
	v_ashrrev_i32_e32 v51, 31, v50
	s_waitcnt lgkmcnt(0)
	v_add_f32_e32 v44, v44, v45
	v_mov_b32_e32 v45, v44
	s_nop 1
	v_permlane16_swap_b32_e32 v45, v44
	s_nop 1
	v_cndmask_b32_e64 v53, v1, v51, s[54:55]
	v_cndmask_b32_e64 v52, v0, v50, s[54:55]
	s_waitcnt lgkmcnt(0)
	v_add_f32_e32 v44, v44, v45
	s_nop 1
	v_mov_b32_dpp v45, v44 row_ror:8 row_mask:0xf bank_mask:0xf
	s_waitcnt lgkmcnt(0)
	v_add_f32_e32 v44, v44, v45
	s_nop 1
	v_mov_b32_dpp v45, v44 row_shl:4 row_mask:0xf bank_mask:0x5
	v_mov_b32_dpp v45, v44 row_shr:4 row_mask:0xf bank_mask:0xa
	s_waitcnt lgkmcnt(0)
	v_add_f32_e32 v44, v44, v45
	s_nop 1
	v_mov_b32_dpp v45, v44 quad_perm:[2,3,0,1] row_mask:0xf bank_mask:0xf
	s_waitcnt lgkmcnt(0)
	v_add_f32_e32 v44, v44, v45
	s_nop 1
	v_mov_b32_dpp v45, v44 quad_perm:[1,0,3,2] row_mask:0xf bank_mask:0xf
	s_and_saveexec_b64 s[54:55], s[38:39]
	s_cbranch_execz .LBB0_605
	ds_read_b128 v[58:61], v189 offset:20496
	ds_read_b128 v[62:65], v189 offset:20480
	s_waitcnt lgkmcnt(0)
	v_add_f32_e32 v44, v44, v45
	v_fmamk_f32 v44, v44, 0x3b800000, v174
	v_rsq_f32_e32 v66, v44
	s_nop 0
	v_pk_mul_f32 v[44:45], v[66:67], v[48:49] op_sel_hi:[0,1]
	s_waitcnt lgkmcnt(0)
	v_pk_mul_f32 v[48:49], v[62:63], v[44:45]
	v_pk_mul_f32 v[44:45], v[66:67], v[46:47] op_sel_hi:[0,1]
	v_pk_mul_f32 v[50:51], v[64:65], v[44:45]
	v_pk_mul_f32 v[44:45], v[66:67], v[56:57] op_sel_hi:[0,1]
	v_pk_mul_f32 v[46:47], v[66:67], v[54:55] op_sel_hi:[0,1]
	v_pk_mul_f32 v[44:45], v[58:59], v[44:45]
	v_pk_mul_f32 v[46:47], v[46:47], v[60:61]
	v_lshlrev_b64 v[58:59], 9, v[52:53]
	v_cvt_pk_bf16_f32 v54, v48, v49
	v_cvt_pk_bf16_f32 v55, v50, v51
	v_cvt_pk_bf16_f32 v56, v44, v45
	v_cvt_pk_bf16_f32 v57, v46, v47
	v_lshl_add_u64 v[58:59], v[88:89], 0, v[58:59]
	global_store_dwordx4 v[58:59], v[54:57], off
	s_and_b64 exec, exec, s[52:53]
	s_cbranch_execz .LBB0_605
	v_readlane_b32 s2, v254, 61
	v_readlane_b32 s3, v254, 62
	v_lshlrev_b32_e32 v56, 10, v143
	v_lshl_add_u32 v54, v146, 1, s2
	v_ashrrev_i32_e32 v55, 31, v54
	v_readlane_b32 s2, v253, 28
	v_lshlrev_b64 v[54:55], 18, v[54:55]
	v_readlane_b32 s3, v253, 29
	v_mov_b32_e32 v57, v2
	s_nop 0
	v_lshl_add_u64 v[54:55], s[2:3], 0, v[54:55]
	v_lshl_add_u64 v[54:55], v[54:55], 0, v[56:57]
	v_lshlrev_b32_e32 v56, 2, v72
	v_lshl_add_u64 v[54:55], v[54:55], 0, v[56:57]
	global_store_dwordx4 v[54:55], v[48:51], off
	global_store_dwordx4 v[54:55], v[44:47], off offset:16
